# critical-wave priority raise: wave 0 (which loads its x tile after grid barrier 3) runs the P3 prologue at s_setprio 2 until the K-loop's own priority toggles take over
# speedup vs baseline: 1.0069x; 1.0046x over previous
.LBB0_363:
	s_or_b64 exec, exec, s[0:1]
	s_waitcnt vmcnt(1)
	v_mov_b32_e32 v144, v254
	s_waitcnt lgkmcnt(0)
	v_cndmask_b32_e64 v240, 0, 1, s[94:95]
	s_barrier
	v_mov_b32_e32 v255, 0x7000
	global_load_dword v255, v255, s[52:53] sc1
	s_cmpk_gt_u32 s2, 0xff
	s_cbranch_scc1 .Lxb_done
	v_readfirstlane_b32 s4, v254
	s_nop 0
	s_lshr_b32 s4, s4, 6
	s_cmp_lg_u32 s4, 0
	s_cbranch_scc1 .Lxb_done
	s_setprio 2
	global_load_dwordx4 v[124:127], v200, s[12:13] nt
	global_load_dwordx4 v[120:123], v200, s[12:13] offset:16 nt
	global_load_dwordx4 v[116:119], v200, s[12:13] offset:128 nt
	global_load_dwordx4 v[112:115], v200, s[12:13] offset:144 nt
	global_load_dwordx4 v[108:111], v201, s[12:13] nt
	global_load_dwordx4 v[104:107], v201, s[12:13] offset:16 nt
	global_load_dwordx4 v[100:103], v201, s[12:13] offset:128 nt
	global_load_dwordx4 v[96:99], v201, s[12:13] offset:144 nt
	global_load_dwordx4 v[92:95], v202, s[12:13] nt
	global_load_dwordx4 v[88:91], v202, s[12:13] offset:16 nt
	global_load_dwordx4 v[84:87], v202, s[12:13] offset:128 nt
	global_load_dwordx4 v[80:83], v202, s[12:13] offset:144 nt
	global_load_dwordx4 v[76:79], v203, s[12:13] nt
	global_load_dwordx4 v[72:75], v203, s[12:13] offset:16 nt
	global_load_dwordx4 v[68:71], v203, s[12:13] offset:128 nt
	global_load_dwordx4 v[64:67], v203, s[12:13] offset:144 nt
	global_load_dwordx4 v[60:63], v204, s[12:13] nt
	global_load_dwordx4 v[56:59], v204, s[12:13] offset:16 nt
	global_load_dwordx4 v[52:55], v204, s[12:13] offset:128 nt
	global_load_dwordx4 v[48:51], v204, s[12:13] offset:144 nt
	global_load_dwordx4 v[44:47], v205, s[12:13] nt
	global_load_dwordx4 v[40:43], v205, s[12:13] offset:16 nt
	global_load_dwordx4 v[36:39], v205, s[12:13] offset:128 nt
	global_load_dwordx4 v[32:35], v205, s[12:13] offset:144 nt
	global_load_dwordx4 v[28:31], v206, s[12:13] nt
	global_load_dwordx4 v[24:27], v206, s[12:13] offset:16 nt
	global_load_dwordx4 v[20:23], v206, s[12:13] offset:128 nt
